# decode queue hands out whole cache pages (six heads, one wave, back to back) for the first two thirds of the tickets, pairs after that
# speedup vs baseline: 1.0134x; 1.0134x over previous
; #define LAS __attribute__((address_space(3)))
; __device__ __forceinline__ unsigned xb_add(unsigned* p, unsigned v) { return __hip_atomic_fetch_add(p, v, __ATOMIC_RELAXED, __HIP_MEMORY_SCOPE_AGENT); }
; __device__ __forceinline__ unsigned xb_xcc_id() { return (unsigned)__builtin_amdgcn_s_getreg((3 << 11) | 20) & 0xFu; }
; __device__ __forceinline__ XcdBarrier xcd_barrier_post(unsigned* bar, volatile LAS unsigned* st) {
;     XcdBarrier b; b.bar = bar; b.x = xb_xcc_id(); b.st = st;
;     if (threadIdx.x == 0) (void)xb_add(&bar[XB_XCNT(b.x)], 1u);
;     return b;
; __global__ void __launch_bounds__(512, 2) mk_fwd(Params P) {
;     extern __shared__ __attribute__((aligned(16))) unsigned char lds[];
;     volatile LAS unsigned* xbw = (volatile LAS unsigned*)((LAS unsigned char*)lds + LDS_CTL);
;     if (threadIdx.x < 4) xbw[threadIdx.x] = 0u;
;     __syncthreads();
;     XcdBarrier bar; bar.bar = (unsigned*)(P.ws + WS_BAR); bar.x = 0; bar.st = xbw;
;     ...
;     bar = xcd_barrier_post((unsigned*)(P.ws + WS_BAR), xbw);
_Z6mk_fwd6Params:
	s_load_dwordx8 s[68:75], s[0:1], 0xc0
	s_load_dwordx4 s[76:79], s[0:1], 0xe0
	s_load_dwordx2 s[60:61], s[0:1], 0xf0
	s_mov_b32 s56, s2
	s_mov_b32 s100, 0
	s_mov_b64 s[58:59], s[0:1]
	v_cmp_gt_u32_e32 vcc, 4, v0
	s_and_saveexec_b64 s[0:1], vcc
	v_lshl_add_u32 v1, v0, 2, 0
	v_add_u32_e32 v1, 0x26000, v1
	v_mov_b32_e32 v2, 0
	ds_write_b32 v1, v2
	s_or_b64 exec, exec, s[0:1]
	s_load_dwordx16 s[0:15], s[58:59], 0x0
	s_waitcnt lgkmcnt(0)
	s_barrier
	v_cmp_eq_u32_e64 s[80:81], 0, v0
	v_writelane_b32 v252, s0, 0
	s_nop 1
	v_writelane_b32 v252, s1, 1
	v_writelane_b32 v252, s2, 2
	v_writelane_b32 v252, s3, 3
	v_writelane_b32 v252, s4, 4
	v_writelane_b32 v252, s5, 5
	v_writelane_b32 v252, s6, 6
	v_writelane_b32 v252, s7, 7
	v_writelane_b32 v252, s8, 8
	v_writelane_b32 v252, s9, 9
	v_writelane_b32 v252, s10, 10
	v_writelane_b32 v252, s11, 11
	v_writelane_b32 v252, s12, 12
	v_writelane_b32 v252, s13, 13
	v_writelane_b32 v252, s14, 14
	v_writelane_b32 v252, s15, 15
	s_getreg_b32 s0, hwreg(HW_REG_XCC_ID, 0, 4)
	s_and_b32 s57, s0, 15
	s_and_saveexec_b64 s[0:1], s[80:81]
	s_cbranch_execz .LBB0_5
	s_mov_b64 s[2:3], exec
	v_mbcnt_lo_u32_b32 v1, s2, 0
	v_mbcnt_hi_u32_b32 v1, s3, v1
	v_cmp_eq_u32_e32 vcc, 0, v1
	s_and_b64 s[4:5], exec, vcc
	s_mov_b64 exec, s[4:5]
	s_cbranch_execz .LBB0_5
	s_lshl_b32 s4, s57, 8
	s_bcnt1_i32_b64 s2, s[2:3]
	v_mov_b32_e32 v1, s4
	v_mov_b32_e32 v2, s2
	global_atomic_add v1, v2, s[78:79] offset:1024

; #define LAS __attribute__((address_space(3)))
; __device__ __forceinline__ unsigned xb_ld(unsigned* p)              { return __hip_atomic_load(p, __ATOMIC_RELAXED, __HIP_MEMORY_SCOPE_AGENT); }
; #define XB_SPIN(cond, bar) do { unsigned _sp = 0; while (cond) { __builtin_amdgcn_s_sleep(1); \
;     if ((++_sp & 255u) == 0u) { if (xb_ld(&(bar)[XB_TMO])) break; if (_sp > XB_SPIN_CAP) { atomicAdd(&(bar)[XB_TMO], 1u); break; } } } } while (0)
; __device__ __forceinline__ void sb_decode_wave_loop(const Params& P, float* lds) {
;     unsigned* qd = (unsigned*)(P.ws + WS_BAR) + QW_DEC;
;     const int lane = threadIdx.x & 63;
;     volatile LAS unsigned* scw = (volatile LAS unsigned*)((LAS unsigned char*)lds + SC_CTL_OFF_FWD);
;     unsigned nxt = 0u;
;     if (lane == 0) nxt = atomicAdd(qd, 2u);
; __device__ __forceinline__ void p3_scan_and_sb(const Params& P, float* lds) {
;     const int tid = threadIdx.x, lane = tid & 63, wave = tid >> 6;
;     unsigned* ctl = (unsigned*)(P.ws + WS_BAR);
;     __syncthreads();
;     if (blockIdx.x < 96) {
;         const int bh = blockIdx.x >> 2, quarter = blockIdx.x & 3, b = bh / RH, h = bh % RH;
;         volatile LAS unsigned* scw = (volatile LAS unsigned*)((LAS unsigned char*)lds + SC_CTL_OFF);
;         if (tid < 5) scw[tid] = 0u;
;         if (tid == 0) { XB_SPIN(xb_ld(ctl + QW_PREP_W) < (unsigned)NPREP, ctl); __builtin_amdgcn_fence(__ATOMIC_ACQUIRE, "agent"); asm volatile("s_waitcnt vmcnt(0)" ::: "memory"); }
;         __syncthreads();
;         scan_prompt_wave(P, (unsigned char*)lds, b, h, quarter);
;         if (wave >= 5 + SC_FREE_WAVES) {
;             constexpr unsigned NCHU = SEQ / SCH;
;             while (scw[1] < NCHU || scw[2] < NCHU || scw[3] < NCHU || scw[4] < NCHU) __builtin_amdgcn_s_sleep(32);
;         }
;     } else {
;         const int grp = wave >> 2, gw = wave & 3;
;         volatile LAS unsigned* gctl = (volatile LAS unsigned*)((LAS unsigned char*)lds + LDS_CTL + 32);
;         if (tid < 8) gctl[tid] = 0u;
;         __syncthreads();
;         sba::Grp4 G; G.ctr = gctl + grp; G.gen = 0u;
;         if (grp == 1) sb_decode_wave_loop(P, lds);
.LBB0_939:
	s_cmp_lt_i32 s60, 4
	s_cselect_b64 s[0:1], -1, 0
	s_cmp_gt_i32 s61, 3
	s_cselect_b64 s[2:3], -1, 0
	s_and_b64 s[34:35], s[0:1], s[2:3]
	s_andn2_b64 vcc, exec, s[34:35]
	s_cbranch_vccnz .LBB0_1576
	v_writelane_b32 v252, s34, 54
	s_cmpk_lt_u32 s56, 0x60
	v_and_b32_e32 v1, 63, v0
	v_writelane_b32 v252, s35, 55
	v_writelane_b32 v252, s80, 56
	s_cselect_b64 s[52:53], -1, 0
	s_cmpk_gt_u32 s56, 0x5f
	v_writelane_b32 v252, s81, 57
	v_writelane_b32 v252, s56, 53
	v_writelane_b32 v252, s60, 51
	s_mov_b64 s[0:1], -1
	s_waitcnt vmcnt(0)
	v_writelane_b32 v252, s61, 52
	s_barrier
	v_writelane_b32 v252, s57, 50
	s_cbranch_scc0 .LBB0_1203
	v_writelane_b32 v252, s52, 58
	v_cmp_gt_u32_e32 vcc, 8, v0
	s_nop 0
	v_writelane_b32 v252, s53, 59
	s_and_saveexec_b64 s[0:1], vcc
	v_lshl_add_u32 v2, v0, 2, 0
	v_add_u32_e32 v2, 0x26020, v2
	v_mov_b32_e32 v3, 0
	ds_write_b32 v2, v3
	s_or_b64 exec, exec, s[0:1]
	v_lshrrev_b32_e32 v94, 8, v0
	s_waitcnt lgkmcnt(0)
	s_barrier
	v_cmp_eq_u32_e32 vcc, 1, v94
	s_mov_b64 s[0:1], exec
	v_writelane_b32 v252, s0, 60
	s_nop 1
	v_writelane_b32 v252, s1, 61
	s_and_b64 s[0:1], s[0:1], vcc
	s_mov_b64 exec, s[0:1]
	s_cbranch_execz .LBB0_1092
	s_add_u32 s0, s78, 0x3900
	s_addc_u32 s1, s79, 0
	v_writelane_b32 v252, s0, 62
	v_mov_b32_e32 v95, 0
	v_cmp_eq_u32_e64 s[4:5], 0, v1
	v_writelane_b32 v252, s1, 63
	s_and_saveexec_b64 s[0:1], s[4:5]
	v_readlane_b32 s22, v252, 48
	v_readlane_b32 s23, v252, 49
	s_cbranch_execz .LBB0_948
	s_mov_b64 s[6:7], exec
	v_mbcnt_lo_u32_b32 v2, s6, 0
	v_mbcnt_hi_u32_b32 v2, s7, v2
	v_cmp_eq_u32_e32 vcc, 0, v2
	s_and_saveexec_b64 s[2:3], vcc
	s_cbranch_execz .LBB0_947
	s_bcnt1_i32_b64 s6, s[6:7]
	s_mul_i32 s6, s6, 6
	s_mov_b32 s99, 3
	v_mov_b32_e32 v4, s6
	v_readlane_b32 s6, v252, 62
	v_mov_b32_e32 v3, 0
	v_readlane_b32 s7, v252, 63
	s_nop 4
	global_atomic_add v3, v3, v4, s[6:7] sc0

; __device__ __forceinline__ void sb_decode_wave_loop(const Params& P, float* lds) {
;     ...
;     for (;;) {
;         const int t = __builtin_amdgcn_readfirstlane((int)nxt);
;         if (t >= DEC_NTASK) break;
;         if (lane == 0) nxt = atomicAdd(qd, 2u);
;         bool thin = false;
;         bool scan_running = false;
;         if (SC_THIN && blockIdx.x < 96) { constexpr unsigned NCHU = SEQ / 16; scan_running = scw[1] < NCHU || scw[2] < NCHU || scw[3] < NCHU || scw[4] < NCHU; thin = scan_running; }
;         thin = true;
;         if (blockIdx.x < 96 && scan_running) { sb_decode_task<4>(P, lds, t); sb_decode_task<4>(P, lds, t + 1); }
;         else if (thin) { sb_decode_task<8>(P, lds, t); sb_decode_task<8>(P, lds, t + 1); }
;         else { sb_decode_task<16>(P, lds, t); sb_decode_task<16>(P, lds, t + 1); }
;     }
.LBB0_949:
	s_or_b64 exec, exec, s[0:1]
	s_mov_b64 s[0:1], 0
	s_add_i32 s100, s100, 1
	s_cmp_lt_u32 s100, s98
	s_cbranch_scc0 .Lsx1_next
	s_add_i32 s34, s34, 1
	s_cmpk_gt_i32 s34, 0x5fff
	s_cbranch_scc1 .Lsx1_next
	s_branch .LBB0_956
.Lsx1_next:
	s_mov_b32 s100, 0

; __device__ __forceinline__ void sb_decode_wave_loop(const Params& P, float* lds) {
;     ...
;     for (;;) {
;         const int t = __builtin_amdgcn_readfirstlane((int)nxt);
;         if (t >= DEC_NTASK) break;
;         if (lane == 0) nxt = atomicAdd(qd, 2u);
.LBB0_951:
	v_readfirstlane_b32 s34, v95
	s_cmpk_gt_i32 s34, 0x5fff
	s_mov_b64 s[0:1], -1
	s_cbranch_scc1 .LBB0_950
	s_mov_b32 s98, s99
	s_cmpk_lt_i32 s34, 0x4000
	s_cselect_b32 s99, 3, 1
	s_and_saveexec_b64 s[0:1], s[4:5]
	s_cbranch_execz .LBB0_956
	s_mov_b64 s[36:37], exec
	v_mbcnt_lo_u32_b32 v2, s36, 0
	v_mbcnt_hi_u32_b32 v2, s37, v2
	v_cmp_eq_u32_e32 vcc, 0, v2
	s_and_saveexec_b64 s[2:3], vcc
	s_cbranch_execz .LBB0_955
	s_bcnt1_i32_b64 s33, s[36:37]
	s_mul_i32 s33, s33, s99
	s_lshl_b32 s33, s33, 1
	v_readlane_b32 s36, v252, 62
	v_mov_b32_e32 v3, s33
	v_readlane_b32 s37, v252, 63
	s_nop 4
	global_atomic_add v254, v83, v3, s[36:37] sc0

; #define LAS __attribute__((address_space(3)))
; __device__ __forceinline__ void sb_decode_wave_loop(const Params& P, float* lds) {
;     unsigned* qd = (unsigned*)(P.ws + WS_BAR) + QW_DEC;
;     const int lane = threadIdx.x & 63;
;     volatile LAS unsigned* scw = (volatile LAS unsigned*)((LAS unsigned char*)lds + SC_CTL_OFF_FWD);
;     unsigned nxt = 0u;
;     if (lane == 0) nxt = atomicAdd(qd, 2u);
; __device__ __forceinline__ void p3_scan_and_sb(const Params& P, float* lds) {
;     ...
;     sb_decode_wave_loop(P, lds);
.LBB0_1261:
	s_add_u32 s0, s78, 0x3900
	s_addc_u32 s1, s79, 0
	v_writelane_b32 v252, s0, 62
	v_mov_b32_e32 v98, 0
	v_cmp_eq_u32_e64 s[4:5], 0, v1
	v_writelane_b32 v252, s1, 63
	s_and_saveexec_b64 s[0:1], s[4:5]
	s_cbranch_execz .LBB0_1265
	s_mov_b64 s[6:7], exec
	v_mbcnt_lo_u32_b32 v2, s6, 0
	v_mbcnt_hi_u32_b32 v2, s7, v2
	v_cmp_eq_u32_e32 vcc, 0, v2
	s_and_saveexec_b64 s[2:3], vcc
	s_cbranch_execz .LBB0_1264
	s_bcnt1_i32_b64 s6, s[6:7]
	s_mul_i32 s6, s6, 6
	s_mov_b32 s99, 3
	v_mov_b32_e32 v4, s6
	v_readlane_b32 s6, v252, 62
	v_mov_b32_e32 v3, 0
	v_readlane_b32 s7, v252, 63
	s_nop 4
	global_atomic_add v3, v3, v4, s[6:7] sc0

; __device__ __forceinline__ void sb_decode_wave_loop(const Params& P, float* lds) {
;     ...
;     for (;;) {
;         const int t = __builtin_amdgcn_readfirstlane((int)nxt);
;         if (t >= DEC_NTASK) break;
;         if (lane == 0) nxt = atomicAdd(qd, 2u);
;         bool thin = false;
;         bool scan_running = false;
;         if (SC_THIN && blockIdx.x < 96) { constexpr unsigned NCHU = SEQ / 16; scan_running = scw[1] < NCHU || scw[2] < NCHU || scw[3] < NCHU || scw[4] < NCHU; thin = scan_running; }
;         thin = true;
;         if (blockIdx.x < 96 && scan_running) { sb_decode_task<4>(P, lds, t); sb_decode_task<4>(P, lds, t + 1); }
;         else if (thin) { sb_decode_task<8>(P, lds, t); sb_decode_task<8>(P, lds, t + 1); }
;         else { sb_decode_task<16>(P, lds, t); sb_decode_task<16>(P, lds, t + 1); }
;     }
.LBB0_1266:
	s_or_b64 exec, exec, s[0:1]
	s_sub_i32 s34, s34, 1
.LBB0_1267:
	s_mov_b64 s[0:1], 0
	s_add_i32 s100, s100, 1
	s_cmp_lt_u32 s100, s98
	s_cbranch_scc0 .Lsx2_next
	s_add_i32 s34, s34, 2
	s_cmpk_gt_i32 s34, 0x5fff
	s_cbranch_scc1 .Lsx2_next
	s_branch .LBB0_1274

; __device__ __forceinline__ void sb_decode_wave_loop(const Params& P, float* lds) {
;     ...
;     for (;;) {
;         const int t = __builtin_amdgcn_readfirstlane((int)nxt);
;         if (t >= DEC_NTASK) break;
;         if (lane == 0) nxt = atomicAdd(qd, 2u);
.LBB0_1269:
	v_readfirstlane_b32 s34, v98
	s_cmpk_gt_i32 s34, 0x5fff
	s_mov_b64 s[0:1], -1
	s_cbranch_scc1 .LBB0_1268
	s_mov_b32 s98, s99
	s_cmpk_lt_i32 s34, 0x4000
	s_cselect_b32 s99, 3, 1
	s_and_saveexec_b64 s[0:1], s[4:5]
	s_cbranch_execz .LBB0_1274
	s_mov_b64 s[36:37], exec
	v_mbcnt_lo_u32_b32 v2, s36, 0
	v_mbcnt_hi_u32_b32 v2, s37, v2
	v_cmp_eq_u32_e32 vcc, 0, v2
	s_and_saveexec_b64 s[2:3], vcc
	s_cbranch_execz .LBB0_1273
	s_bcnt1_i32_b64 s33, s[36:37]
	s_mul_i32 s33, s33, s99
	s_lshl_b32 s33, s33, 1
	v_readlane_b32 s30, v252, 62
	v_mov_b32_e32 v3, s33
	v_readlane_b32 s31, v252, 63
	s_nop 4
	global_atomic_add v254, v83, v3, s[30:31] sc0
